# up GEMM: next unit's first-superphase half-tile staged at epilogue entry; first K-iteration skips the vmcnt waits that drained the output stores
# baseline (speedup 1.0000x reference)
.LBB0_1170:
	v_lshrrev_b32_e32 v16, 1, v14
	s_lshl_b32 s6, s40, 4
	s_mul_i32 s9, s64, 0x44000
	v_readlane_b32 s10, v254, 2
	v_and_b32_e32 v16, 24, v16
	s_mul_hi_i32 s8, s64, 0x44000
	s_add_u32 s35, s10, s9
	v_readlane_b32 s9, v254, 3
	v_and_b32_e32 v15, 15, v14
	v_lshlrev_b32_e32 v17, 1, v16
	v_lshlrev_b32_e32 v14, 2, v14
	s_addc_u32 s50, s9, s8
	v_lshl_or_b32 v176, s3, 6, v15
	v_lshl_or_b32 v15, v15, 6, v17
	s_lshl_b32 s3, s3, 13
	v_and_b32_e32 v14, 32, v14
	v_bitop3_b32 v17, v15, s3, v14 bitop3:0xde
	s_lshl_b32 s3, s7, 5
	s_and_b32 s3, s3, 0x60
	s_add_i32 m0, s28, 0x18000
	v_lshl_add_u64 v[6:7], v[6:7], 0, s[44:45]
	s_lshl_b32 s7, s3, 7
	s_waitcnt vmcnt(2)
	s_barrier
	global_load_lds_dwordx4 v[6:7], off
	v_lshl_add_u64 v[4:5], v[4:5], 0, s[44:45]
	s_add_i32 m0, s28, 0x1a000
	s_add_i32 s51, s28, 0x8000
	s_add_i32 s53, s28, 0xa000
	global_load_lds_dwordx4 v[4:5], off
	v_lshl_add_u64 v[0:1], v[0:1], 0, s[44:45]
	s_mov_b32 m0, s51
	s_add_u32 s8, s20, 0x40080
	global_load_lds_dwordx4 v[0:1], off
	v_lshl_add_u64 v[0:1], v[2:3], 0, s[44:45]
	s_mov_b32 m0, s53
	s_addc_u32 s9, s21, 0
	global_load_lds_dwordx4 v[0:1], off
	s_add_i32 m0, s28, 0x1c000
	v_lshl_add_u64 v[0:1], s[8:9], 0, v[152:153]
	global_load_lds_dwordx4 v[0:1], off
	v_lshl_add_u64 v[0:1], s[8:9], 0, v[148:149]
	s_add_i32 m0, s28, 0x1e000
	s_cmpk_lt_u32 s2, 0x100
	global_load_lds_dwordx4 v[0:1], off
	v_lshlrev_b32_e32 v0, 14, v8
	v_and_b32_e32 v0, 0xffff8000, v0
	v_lshl_add_u32 v0, v9, 11, v0
	v_and_b32_e32 v1, 1, v8
	v_lshl_or_b32 v0, v1, 6, v0
	v_lshl_add_u32 v150, v10, 1, v0
	v_lshlrev_b32_e32 v0, 14, v11
	v_and_b32_e32 v0, 0xffff8000, v0
	s_waitcnt vmcnt(6)
	v_lshl_add_u32 v0, v12, 11, v0
	v_and_b32_e32 v1, 1, v11
	v_lshl_or_b32 v0, v1, 6, v0
	v_bitop3_b32 v177, v15, s7, v14 bitop3:0xde
	s_cselect_b64 s[8:9], -1, 0
	s_mov_b32 s7, s49
	v_or_b32_e32 v178, s3, v16
	v_mov_b32_e32 v151, v153
	v_lshl_add_u32 v166, v13, 1, v0
	v_mov_b32_e32 v167, v153
	s_mov_b32 s48, 0
	v_add_u32_e32 v179, 0, v17
	s_add_u32 s100, s18, 0x40080
	s_addc_u32 s101, s19, 0
	v_lshl_add_u64 v[0:1], s[100:101], 0, v[150:151]
	s_add_i32 m0, s28, 0xc000
	s_nop 0
	global_load_lds_dwordx4 v[0:1], off
	v_lshl_add_u64 v[0:1], s[100:101], 0, v[166:167]
	s_add_i32 m0, s28, 0xe000
	s_nop 0
	global_load_lds_dwordx4 v[0:1], off
	s_waitcnt vmcnt(0)
	s_barrier
	s_branch .LBB0_1173

.LBB0_1176:
	v_add_u32_e32 v84, s63, v177
	v_add_u32_e32 v162, s91, v177
	ds_read_b128 v[72:75], v84
	ds_read_b128 v[76:79], v84 offset:1024
	ds_read_b128 v[80:83], v84 offset:2048
	ds_read_b128 v[84:87], v84 offset:3072
	ds_read_b128 v[154:157], v162
	ds_read_b128 v[158:161], v162 offset:1024
	ds_read_b128 v[168:171], v162 offset:2048
	ds_read_b128 v[172:175], v162 offset:3072
	s_add_u32 s20, s18, 0xfffc0080
	s_addc_u32 s21, s19, -1
	s_cmp_eq_u32 s64, 12
	s_cselect_b32 s23, s13, s21
	s_cselect_b32 s22, s94, s20
	s_cselect_b32 s21, s11, s85
	s_cselect_b32 s20, s95, s84
	v_lshl_add_u64 v[200:201], s[18:19], 0, v[150:151]
	s_add_i32 m0, s28, 0xc000
	ds_read_b128 v[180:183], v179
	ds_read_b128 v[184:187], v179 offset:1024
	ds_read_b128 v[188:191], v179 offset:2048
	ds_read_b128 v[192:195], v179 offset:3072
	ds_read_b128 v[196:199], v179 offset:4096
	ds_read_b128 v[208:211], v179 offset:5120
	ds_read_b128 v[212:215], v179 offset:6144
	ds_read_b128 v[216:219], v179 offset:7168
	s_cmp_eq_u32 s64, -2
	s_cbranch_scc1 .Lupf_l0
	global_load_lds_dwordx4 v[200:201], off
.Lupf_l0:
	v_lshl_add_u64 v[200:201], s[18:19], 0, v[166:167]
	s_add_i32 m0, s28, 0xe000
	s_nop 0
	s_cmp_eq_u32 s64, -2
	s_cbranch_scc1 .Lupf_l1
	global_load_lds_dwordx4 v[200:201], off
.Lupf_l1:
	s_cmp_eq_u32 s64, -2
	s_cbranch_scc1 .Lupf_w0
	s_waitcnt vmcnt(8)
.Lupf_w0:
	s_waitcnt lgkmcnt(0)
	s_barrier
	s_setprio 1
	s_waitcnt lgkmcnt(0)
	v_mfma_f32_16x16x32_bf16 v[140:143], v[72:75], v[180:183], v[140:143]
	v_mfma_f32_16x16x32_bf16 v[136:139], v[80:83], v[180:183], v[136:139]
	v_mfma_f32_16x16x32_bf16 v[124:127], v[72:75], v[188:191], v[124:127]
	v_mfma_f32_16x16x32_bf16 v[120:123], v[80:83], v[188:191], v[120:123]
	v_mfma_f32_16x16x32_bf16 v[108:111], v[72:75], v[196:199], v[108:111]
	v_mfma_f32_16x16x32_bf16 v[104:107], v[80:83], v[196:199], v[104:107]
	v_mfma_f32_16x16x32_bf16 v[92:95], v[72:75], v[212:215], v[92:95]
	v_mfma_f32_16x16x32_bf16 v[88:91], v[80:83], v[212:215], v[88:91]
	v_mfma_f32_16x16x32_bf16 v[140:143], v[76:79], v[184:187], v[140:143]
	v_mfma_f32_16x16x32_bf16 v[136:139], v[84:87], v[184:187], v[136:139]
	v_mfma_f32_16x16x32_bf16 v[124:127], v[76:79], v[192:195], v[124:127]
	v_mfma_f32_16x16x32_bf16 v[120:123], v[84:87], v[192:195], v[120:123]
	v_mfma_f32_16x16x32_bf16 v[108:111], v[76:79], v[208:211], v[108:111]
	v_mfma_f32_16x16x32_bf16 v[104:107], v[84:87], v[208:211], v[104:107]
	v_mfma_f32_16x16x32_bf16 v[92:95], v[76:79], v[216:219], v[92:95]
	v_mfma_f32_16x16x32_bf16 v[88:91], v[84:87], v[216:219], v[88:91]
	s_setprio 0
	s_setprio 1
	v_mfma_f32_16x16x32_bf16 v[132:135], v[154:157], v[180:183], v[132:135]
	v_mfma_f32_16x16x32_bf16 v[128:131], v[168:171], v[180:183], v[128:131]
	v_mfma_f32_16x16x32_bf16 v[116:119], v[154:157], v[188:191], v[116:119]
	v_mfma_f32_16x16x32_bf16 v[112:115], v[168:171], v[188:191], v[112:115]
	v_mfma_f32_16x16x32_bf16 v[100:103], v[154:157], v[196:199], v[100:103]
	v_mfma_f32_16x16x32_bf16 v[96:99], v[168:171], v[196:199], v[96:99]
	v_mfma_f32_16x16x32_bf16 v[68:71], v[154:157], v[212:215], v[68:71]
	v_mfma_f32_16x16x32_bf16 v[64:67], v[168:171], v[212:215], v[64:67]
	v_mfma_f32_16x16x32_bf16 v[132:135], v[158:161], v[184:187], v[132:135]
	v_mfma_f32_16x16x32_bf16 v[128:131], v[172:175], v[184:187], v[128:131]
	v_mfma_f32_16x16x32_bf16 v[116:119], v[158:161], v[192:195], v[116:119]
	v_mfma_f32_16x16x32_bf16 v[112:115], v[172:175], v[192:195], v[112:115]
	v_mfma_f32_16x16x32_bf16 v[100:103], v[158:161], v[208:211], v[100:103]
	v_mfma_f32_16x16x32_bf16 v[96:99], v[172:175], v[208:211], v[96:99]
	v_mfma_f32_16x16x32_bf16 v[68:71], v[158:161], v[216:219], v[68:71]
	v_mfma_f32_16x16x32_bf16 v[64:67], v[172:175], v[216:219], v[64:67]
	s_setprio 0
	s_barrier
	s_add_i32 s65, s63, s26
	v_lshl_add_u64 v[200:201], s[20:21], 0, v[152:153]
	s_mov_b32 m0, s65
	ds_read_b128 v[180:183], v179 offset:16384
	ds_read_b128 v[184:187], v179 offset:17408
	ds_read_b128 v[188:191], v179 offset:18432
	ds_read_b128 v[192:195], v179 offset:19456
	ds_read_b128 v[196:199], v179 offset:20480
	ds_read_b128 v[208:211], v179 offset:21504
	ds_read_b128 v[212:215], v179 offset:22528
	ds_read_b128 v[216:219], v179 offset:23552
	global_load_lds_dwordx4 v[200:201], off
	s_add_i32 m0, s65, 0x2000
	s_add_u32 s78, s20, 0x40000
	v_lshl_add_u64 v[220:221], s[20:21], 0, v[148:149]
	s_addc_u32 s79, s21, 0
	s_add_i32 s65, s91, s26
	global_load_lds_dwordx4 v[220:221], off
	v_lshl_add_u64 v[222:223], s[78:79], 0, v[152:153]
	s_mov_b32 m0, s65
	v_lshl_add_u64 v[224:225], s[22:23], 0, v[146:147]
	global_load_lds_dwordx4 v[222:223], off
	v_lshl_add_u64 v[222:223], s[78:79], 0, v[148:149]
	s_add_i32 m0, s65, 0x2000
	s_nop 0
	global_load_lds_dwordx4 v[222:223], off
	v_lshl_add_u64 v[222:223], s[22:23], 0, v[144:145]
	s_mov_b32 m0, s28
	s_nop 0
	global_load_lds_dwordx4 v[222:223], off
	s_mov_b32 m0, s29
	s_nop 0
	global_load_lds_dwordx4 v[224:225], off
	s_cmp_eq_u32 s64, -2
	s_cbranch_scc1 .Lupf_w1
	s_waitcnt vmcnt(8)
.Lupf_w1:
	s_waitcnt lgkmcnt(0)
	s_barrier
	s_setprio 1
	s_waitcnt lgkmcnt(0)
	v_mfma_f32_16x16x32_bf16 v[60:63], v[72:75], v[180:183], v[60:63]
	v_mfma_f32_16x16x32_bf16 v[56:59], v[80:83], v[180:183], v[56:59]
	v_mfma_f32_16x16x32_bf16 v[44:47], v[72:75], v[188:191], v[44:47]
	v_mfma_f32_16x16x32_bf16 v[40:43], v[80:83], v[188:191], v[40:43]
	v_mfma_f32_16x16x32_bf16 v[28:31], v[72:75], v[196:199], v[28:31]
	v_mfma_f32_16x16x32_bf16 v[24:27], v[80:83], v[196:199], v[24:27]
	v_mfma_f32_16x16x32_bf16 v[12:15], v[72:75], v[212:215], v[12:15]
	v_mfma_f32_16x16x32_bf16 v[8:11], v[80:83], v[212:215], v[8:11]
	v_mfma_f32_16x16x32_bf16 v[60:63], v[76:79], v[184:187], v[60:63]
	v_mfma_f32_16x16x32_bf16 v[56:59], v[84:87], v[184:187], v[56:59]
	v_mfma_f32_16x16x32_bf16 v[44:47], v[76:79], v[192:195], v[44:47]
	v_mfma_f32_16x16x32_bf16 v[40:43], v[84:87], v[192:195], v[40:43]
	v_mfma_f32_16x16x32_bf16 v[28:31], v[76:79], v[208:211], v[28:31]
	v_mfma_f32_16x16x32_bf16 v[24:27], v[84:87], v[208:211], v[24:27]
	v_mfma_f32_16x16x32_bf16 v[12:15], v[76:79], v[216:219], v[12:15]
	v_mfma_f32_16x16x32_bf16 v[8:11], v[84:87], v[216:219], v[8:11]
	s_setprio 0
	s_setprio 1
	v_mfma_f32_16x16x32_bf16 v[52:55], v[154:157], v[180:183], v[52:55]
	v_mfma_f32_16x16x32_bf16 v[48:51], v[168:171], v[180:183], v[48:51]
	v_mfma_f32_16x16x32_bf16 v[36:39], v[154:157], v[188:191], v[36:39]
	v_mfma_f32_16x16x32_bf16 v[32:35], v[168:171], v[188:191], v[32:35]
	v_mfma_f32_16x16x32_bf16 v[20:23], v[154:157], v[196:199], v[20:23]
	v_mfma_f32_16x16x32_bf16 v[16:19], v[168:171], v[196:199], v[16:19]
	v_mfma_f32_16x16x32_bf16 v[4:7], v[154:157], v[212:215], v[4:7]
	v_mfma_f32_16x16x32_bf16 v[0:3], v[168:171], v[212:215], v[0:3]
	v_mfma_f32_16x16x32_bf16 v[52:55], v[158:161], v[184:187], v[52:55]
	v_mfma_f32_16x16x32_bf16 v[48:51], v[172:175], v[184:187], v[48:51]
	v_mfma_f32_16x16x32_bf16 v[36:39], v[158:161], v[192:195], v[36:39]
	v_mfma_f32_16x16x32_bf16 v[32:35], v[172:175], v[192:195], v[32:35]
	v_mfma_f32_16x16x32_bf16 v[20:23], v[158:161], v[208:211], v[20:23]
	v_mfma_f32_16x16x32_bf16 v[16:19], v[172:175], v[208:211], v[16:19]
	v_mfma_f32_16x16x32_bf16 v[4:7], v[158:161], v[216:219], v[4:7]
	v_mfma_f32_16x16x32_bf16 v[0:3], v[172:175], v[216:219], v[0:3]
	s_setprio 0
	s_barrier
	v_add_u32_e32 v84, s41, v177
	v_add_u32_e32 v162, s57, v177
	ds_read_b128 v[72:75], v84
	ds_read_b128 v[76:79], v84 offset:1024
	ds_read_b128 v[80:83], v84 offset:2048
	ds_read_b128 v[84:87], v84 offset:3072
	ds_read_b128 v[154:157], v162
	ds_read_b128 v[158:161], v162 offset:1024
	ds_read_b128 v[168:171], v162 offset:2048
	ds_read_b128 v[172:175], v162 offset:3072
	s_add_u32 s22, s22, 0x40000
	s_addc_u32 s23, s23, 0
	s_mov_b32 m0, s30
	v_lshl_add_u64 v[226:227], s[22:23], 0, v[144:145]
	ds_read_b128 v[180:183], v179 offset:32768
	ds_read_b128 v[184:187], v179 offset:33792
	ds_read_b128 v[188:191], v179 offset:34816
	ds_read_b128 v[192:195], v179 offset:35840
	ds_read_b128 v[196:199], v179 offset:36864
	ds_read_b128 v[208:211], v179 offset:37888
	ds_read_b128 v[212:215], v179 offset:38912
	ds_read_b128 v[216:219], v179 offset:39936
	global_load_lds_dwordx4 v[226:227], off
	v_lshl_add_u64 v[226:227], s[22:23], 0, v[146:147]
	s_mov_b32 m0, s31
	s_nop 0
	global_load_lds_dwordx4 v[226:227], off
	s_cmp_eq_u32 s64, -2
	s_cbranch_scc1 .Lupf_w2
	s_waitcnt vmcnt(8)
.Lupf_w2:
	s_waitcnt lgkmcnt(0)
	s_barrier
	s_setprio 1
	s_waitcnt lgkmcnt(0)
	v_mfma_f32_16x16x32_bf16 v[140:143], v[72:75], v[180:183], v[140:143]
	v_mfma_f32_16x16x32_bf16 v[136:139], v[80:83], v[180:183], v[136:139]
	v_mfma_f32_16x16x32_bf16 v[124:127], v[72:75], v[188:191], v[124:127]
	v_mfma_f32_16x16x32_bf16 v[120:123], v[80:83], v[188:191], v[120:123]
	v_mfma_f32_16x16x32_bf16 v[108:111], v[72:75], v[196:199], v[108:111]
	v_mfma_f32_16x16x32_bf16 v[104:107], v[80:83], v[196:199], v[104:107]
	v_mfma_f32_16x16x32_bf16 v[92:95], v[72:75], v[212:215], v[92:95]
	v_mfma_f32_16x16x32_bf16 v[88:91], v[80:83], v[212:215], v[88:91]
	v_mfma_f32_16x16x32_bf16 v[140:143], v[76:79], v[184:187], v[140:143]
	v_mfma_f32_16x16x32_bf16 v[136:139], v[84:87], v[184:187], v[136:139]
	v_mfma_f32_16x16x32_bf16 v[124:127], v[76:79], v[192:195], v[124:127]
	v_mfma_f32_16x16x32_bf16 v[120:123], v[84:87], v[192:195], v[120:123]
	v_mfma_f32_16x16x32_bf16 v[108:111], v[76:79], v[208:211], v[108:111]
	v_mfma_f32_16x16x32_bf16 v[104:107], v[84:87], v[208:211], v[104:107]
	v_mfma_f32_16x16x32_bf16 v[92:95], v[76:79], v[216:219], v[92:95]
	v_mfma_f32_16x16x32_bf16 v[88:91], v[84:87], v[216:219], v[88:91]
	s_setprio 0
	s_setprio 1
	v_mfma_f32_16x16x32_bf16 v[132:135], v[154:157], v[180:183], v[132:135]
	v_mfma_f32_16x16x32_bf16 v[128:131], v[168:171], v[180:183], v[128:131]
	v_mfma_f32_16x16x32_bf16 v[116:119], v[154:157], v[188:191], v[116:119]
	v_mfma_f32_16x16x32_bf16 v[112:115], v[168:171], v[188:191], v[112:115]
	v_mfma_f32_16x16x32_bf16 v[100:103], v[154:157], v[196:199], v[100:103]
	v_mfma_f32_16x16x32_bf16 v[96:99], v[168:171], v[196:199], v[96:99]
	v_mfma_f32_16x16x32_bf16 v[68:71], v[154:157], v[212:215], v[68:71]
	v_mfma_f32_16x16x32_bf16 v[64:67], v[168:171], v[212:215], v[64:67]
	v_mfma_f32_16x16x32_bf16 v[132:135], v[158:161], v[184:187], v[132:135]
	v_mfma_f32_16x16x32_bf16 v[128:131], v[172:175], v[184:187], v[128:131]
	v_mfma_f32_16x16x32_bf16 v[116:119], v[158:161], v[192:195], v[116:119]
	v_mfma_f32_16x16x32_bf16 v[112:115], v[172:175], v[192:195], v[112:115]
	v_mfma_f32_16x16x32_bf16 v[100:103], v[158:161], v[208:211], v[100:103]
	v_mfma_f32_16x16x32_bf16 v[96:99], v[172:175], v[208:211], v[96:99]
	v_mfma_f32_16x16x32_bf16 v[68:71], v[158:161], v[216:219], v[68:71]
	v_mfma_f32_16x16x32_bf16 v[64:67], v[172:175], v[216:219], v[64:67]
	s_setprio 0
	s_barrier
	s_add_i32 s22, s41, s26
	v_lshl_add_u64 v[200:201], v[200:201], 0, s[44:45]
	s_mov_b32 m0, s22
	ds_read_b128 v[180:183], v179 offset:49152
	ds_read_b128 v[184:187], v179 offset:50176
	ds_read_b128 v[188:191], v179 offset:51200
	ds_read_b128 v[192:195], v179 offset:52224
	ds_read_b128 v[196:199], v179 offset:53248
	ds_read_b128 v[208:211], v179 offset:54272
	ds_read_b128 v[212:215], v179 offset:55296
	ds_read_b128 v[216:219], v179 offset:56320
	global_load_lds_dwordx4 v[200:201], off
	s_add_i32 m0, s22, 0x2000
	s_add_u32 s20, s20, 0x40080
	v_lshl_add_u64 v[200:201], v[220:221], 0, s[44:45]
	s_addc_u32 s21, s21, 0
	s_add_i32 s22, s57, s26
	global_load_lds_dwordx4 v[200:201], off
	v_lshl_add_u64 v[200:201], s[20:21], 0, v[152:153]
	s_mov_b32 m0, s22
	s_nop 0
	global_load_lds_dwordx4 v[200:201], off
	v_lshl_add_u64 v[200:201], s[20:21], 0, v[148:149]
	s_add_i32 m0, s22, 0x2000
	s_nop 0
	global_load_lds_dwordx4 v[200:201], off
	v_lshl_add_u64 v[200:201], v[222:223], 0, s[44:45]
	s_mov_b32 m0, s51
	s_nop 0
	global_load_lds_dwordx4 v[200:201], off
	v_lshl_add_u64 v[200:201], v[224:225], 0, s[44:45]
	s_mov_b32 m0, s53
	s_nop 0
	global_load_lds_dwordx4 v[200:201], off
	s_waitcnt vmcnt(8)
	s_waitcnt lgkmcnt(0)
	s_barrier
	s_setprio 1
	s_waitcnt lgkmcnt(0)
	v_mfma_f32_16x16x32_bf16 v[60:63], v[72:75], v[180:183], v[60:63]
	v_mfma_f32_16x16x32_bf16 v[56:59], v[80:83], v[180:183], v[56:59]
	v_mfma_f32_16x16x32_bf16 v[44:47], v[72:75], v[188:191], v[44:47]
	v_mfma_f32_16x16x32_bf16 v[40:43], v[80:83], v[188:191], v[40:43]
	v_mfma_f32_16x16x32_bf16 v[28:31], v[72:75], v[196:199], v[28:31]
	v_mfma_f32_16x16x32_bf16 v[24:27], v[80:83], v[196:199], v[24:27]
	v_mfma_f32_16x16x32_bf16 v[12:15], v[72:75], v[212:215], v[12:15]
	v_mfma_f32_16x16x32_bf16 v[8:11], v[80:83], v[212:215], v[8:11]
	v_mfma_f32_16x16x32_bf16 v[60:63], v[76:79], v[184:187], v[60:63]
	v_mfma_f32_16x16x32_bf16 v[56:59], v[84:87], v[184:187], v[56:59]
	v_mfma_f32_16x16x32_bf16 v[44:47], v[76:79], v[192:195], v[44:47]
	v_mfma_f32_16x16x32_bf16 v[40:43], v[84:87], v[192:195], v[40:43]
	v_mfma_f32_16x16x32_bf16 v[28:31], v[76:79], v[208:211], v[28:31]
	v_mfma_f32_16x16x32_bf16 v[24:27], v[84:87], v[208:211], v[24:27]
	v_mfma_f32_16x16x32_bf16 v[12:15], v[76:79], v[216:219], v[12:15]
	v_mfma_f32_16x16x32_bf16 v[8:11], v[84:87], v[216:219], v[8:11]
	s_setprio 0
	s_setprio 1
	v_mfma_f32_16x16x32_bf16 v[52:55], v[154:157], v[180:183], v[52:55]
	v_mfma_f32_16x16x32_bf16 v[48:51], v[168:171], v[180:183], v[48:51]
	v_mfma_f32_16x16x32_bf16 v[36:39], v[154:157], v[188:191], v[36:39]
	v_mfma_f32_16x16x32_bf16 v[32:35], v[168:171], v[188:191], v[32:35]
	v_mfma_f32_16x16x32_bf16 v[20:23], v[154:157], v[196:199], v[20:23]
	v_mfma_f32_16x16x32_bf16 v[16:19], v[168:171], v[196:199], v[16:19]
	v_mfma_f32_16x16x32_bf16 v[4:7], v[154:157], v[212:215], v[4:7]
	v_mfma_f32_16x16x32_bf16 v[0:3], v[168:171], v[212:215], v[0:3]
	v_mfma_f32_16x16x32_bf16 v[52:55], v[158:161], v[184:187], v[52:55]
	v_mfma_f32_16x16x32_bf16 v[48:51], v[172:175], v[184:187], v[48:51]
	v_mfma_f32_16x16x32_bf16 v[36:39], v[158:161], v[192:195], v[36:39]
	v_mfma_f32_16x16x32_bf16 v[32:35], v[172:175], v[192:195], v[32:35]
	v_mfma_f32_16x16x32_bf16 v[20:23], v[158:161], v[208:211], v[20:23]
	v_mfma_f32_16x16x32_bf16 v[16:19], v[172:175], v[208:211], v[16:19]
	v_mfma_f32_16x16x32_bf16 v[4:7], v[158:161], v[216:219], v[4:7]
	v_mfma_f32_16x16x32_bf16 v[0:3], v[172:175], v[216:219], v[0:3]
	s_setprio 0
	s_barrier
	s_add_i32 s64, s64, 2
	s_add_u32 s18, s18, 0x100
	s_addc_u32 s19, s19, 0
	s_add_u32 s84, s84, 0x100
	s_addc_u32 s85, s85, 0
	s_cmp_gt_u32 s64, 13
	s_cbranch_scc0 .LBB0_1176
	s_and_b64 vcc, exec, s[8:9]
	s_cbranch_vccz .LBB0_1179
	s_barrier
.LBB0_1179:
	s_add_u32 s100, s94, 0x40080
	s_addc_u32 s101, s13, 0
	v_lshl_add_u64 v[200:201], s[100:101], 0, v[150:151]
	s_add_i32 m0, s28, 0xc000
	s_nop 0
	global_load_lds_dwordx4 v[200:201], off
	v_lshl_add_u64 v[200:201], s[100:101], 0, v[166:167]
	s_add_i32 m0, s28, 0xe000
	s_nop 0
	global_load_lds_dwordx4 v[200:201], off
	s_ashr_i32 s18, s56, 3
	v_lshl_add_u32 v172, s56, 8, v176
	s_ashr_i32 s19, s18, 31
	v_ashrrev_i32_e32 v173, 31, v172
	s_lshl_b64 s[18:19], s[18:19], 12
	v_lshl_add_u64 v[170:171], v[172:173], 2, s[54:55]
	s_cmpk_lt_i32 s56, 0x80
	global_load_dword v158, v[170:171], off
	global_load_dword v184, v[170:171], off offset:64
	global_load_dword v185, v[170:171], off offset:128
	global_load_dword v186, v[170:171], off offset:192
	global_load_dword v187, v[170:171], off offset:512
	global_load_dword v188, v[170:171], off offset:576
	global_load_dword v189, v[170:171], off offset:640
	global_load_dword v190, v[170:171], off offset:704
	s_cselect_b32 s19, s19, 0
	s_cselect_b32 s18, s18, 0x10000
	s_lshl_b64 s[18:19], s[18:19], 2
	v_lshl_or_b32 v154, s89, 8, v178
	s_add_u32 s18, s35, s18
	s_addc_u32 s19, s50, s19
	v_ashrrev_i32_e32 v155, 31, v154
	v_lshl_add_u64 v[72:73], v[154:155], 2, s[18:19]
	global_load_dwordx4 v[84:87], v[72:73], off
	global_load_dwordx4 v[80:83], v[72:73], off offset:16
	global_load_dwordx4 v[76:79], v[72:73], off offset:512
	s_nop 0
	global_load_dwordx4 v[72:75], v[72:73], off offset:528
	v_lshlrev_b64 v[156:157], 13, v[172:173]
	v_lshlrev_b64 v[174:175], 1, v[154:155]
	v_lshl_add_u64 v[154:155], s[70:71], 0, v[156:157]
	v_lshl_add_u64 v[168:169], v[154:155], 0, v[174:175]
	s_mov_b32 s11, 0x100000
	s_mov_b64 s[18:19], 0x100000
	v_readlane_b32 s94, v255, 32
	v_readlane_b32 s95, v255, 33
	s_waitcnt vmcnt(0)
	v_mbcnt_lo_u32_b32 v193, -1, 0
	v_mbcnt_hi_u32_b32 v193, -1, v193
	v_and_b32_e32 v194, 15, v193
	v_lshrrev_b32_e32 v195, 2, v193
	v_sub_u32_e32 v195, v195, v194
	v_add_u32_e32 v195, v172, v195
	v_lshrrev_b32_e32 v196, 4, v193
	v_and_b32_e32 v197, 3, v193
	v_sub_u32_e32 v197, v197, v196
	v_lshl_add_u32 v197, v197, 4, v174
	v_lshl_add_u32 v191, v195, 13, v197
	v_and_b32_e32 v198, 3, v193
	v_lshrrev_b32_e32 v199, 2, v193
	v_lshl_add_u32 v198, v198, 4, v199
	v_lshlrev_b32_e32 v198, 2, v198
	s_mov_b64 s[18:19], s[70:71]
	v_fmamk_f32 v158, v158, 0x3a800000, v228
	v_fmamk_f32 v184, v184, 0x3a800000, v228
	v_fmamk_f32 v185, v185, 0x3a800000, v228
	v_fmamk_f32 v186, v186, 0x3a800000, v228
	v_fmamk_f32 v187, v187, 0x3a800000, v228
	v_fmamk_f32 v188, v188, 0x3a800000, v228
	v_fmamk_f32 v189, v189, 0x3a800000, v228
	v_fmamk_f32 v190, v190, 0x3a800000, v228
	v_rsq_f32_e32 v158, v158
	v_rsq_f32_e32 v184, v184
	v_rsq_f32_e32 v185, v185
	v_rsq_f32_e32 v186, v186
	v_rsq_f32_e32 v187, v187
	v_rsq_f32_e32 v188, v188
	v_rsq_f32_e32 v189, v189
	v_rsq_f32_e32 v190, v190
	s_nop 0
	v_mov_b32_e32 v192, v158
	v_pk_fma_f32 v[140:141], v[140:141], v[192:193], v[84:85] op_sel_hi:[1,0,1]
	v_pk_fma_f32 v[142:143], v[142:143], v[192:193], v[86:87] op_sel_hi:[1,0,1]
	v_pk_fma_f32 v[136:137], v[136:137], v[192:193], v[80:81] op_sel_hi:[1,0,1]
	v_pk_fma_f32 v[138:139], v[138:139], v[192:193], v[82:83] op_sel_hi:[1,0,1]
	v_pk_fma_f32 v[132:133], v[132:133], v[192:193], v[76:77] op_sel_hi:[1,0,1]
	v_pk_fma_f32 v[134:135], v[134:135], v[192:193], v[78:79] op_sel_hi:[1,0,1]
	v_pk_fma_f32 v[128:129], v[128:129], v[192:193], v[72:73] op_sel_hi:[1,0,1]
	v_pk_fma_f32 v[130:131], v[130:131], v[192:193], v[74:75] op_sel_hi:[1,0,1]
	v_max_f32_e32 v140, 0, v140
	v_max_f32_e32 v141, 0, v141
	v_max_f32_e32 v142, 0, v142
	v_max_f32_e32 v143, 0, v143
	v_max_f32_e32 v136, 0, v136
	v_max_f32_e32 v137, 0, v137
	v_max_f32_e32 v138, 0, v138
	v_max_f32_e32 v139, 0, v139
	v_max_f32_e32 v132, 0, v132
	v_max_f32_e32 v133, 0, v133
	v_max_f32_e32 v134, 0, v134
	v_max_f32_e32 v135, 0, v135
	v_max_f32_e32 v128, 0, v128
	v_max_f32_e32 v129, 0, v129
	v_max_f32_e32 v130, 0, v130
	v_max_f32_e32 v131, 0, v131
	v_pk_mul_f32 v[140:141], v[140:141], v[140:141]
	v_pk_mul_f32 v[142:143], v[142:143], v[142:143]
	v_pk_mul_f32 v[136:137], v[136:137], v[136:137]
	v_pk_mul_f32 v[138:139], v[138:139], v[138:139]
	v_pk_mul_f32 v[132:133], v[132:133], v[132:133]
	v_pk_mul_f32 v[134:135], v[134:135], v[134:135]
	v_pk_mul_f32 v[128:129], v[128:129], v[128:129]
	v_pk_mul_f32 v[130:131], v[130:131], v[130:131]
	v_cvt_pk_bf16_f32 v140, v140, v141
	v_cvt_pk_bf16_f32 v141, v142, v143
	v_cvt_pk_bf16_f32 v142, v136, v137
	v_cvt_pk_bf16_f32 v143, v138, v139
	v_cvt_pk_bf16_f32 v132, v132, v133
	v_cvt_pk_bf16_f32 v133, v134, v135
	v_cvt_pk_bf16_f32 v134, v128, v129
	v_cvt_pk_bf16_f32 v135, v130, v131
	ds_bpermute_b32 v216, v198, v140
	ds_bpermute_b32 v217, v198, v141
	ds_bpermute_b32 v218, v198, v142
	ds_bpermute_b32 v219, v198, v143
	ds_bpermute_b32 v220, v198, v132
	ds_bpermute_b32 v221, v198, v133
	ds_bpermute_b32 v222, v198, v134
	ds_bpermute_b32 v223, v198, v135
	v_mov_b32_e32 v192, v184
	v_pk_fma_f32 v[124:125], v[124:125], v[192:193], v[84:85] op_sel_hi:[1,0,1]
	v_pk_fma_f32 v[126:127], v[126:127], v[192:193], v[86:87] op_sel_hi:[1,0,1]
	v_pk_fma_f32 v[120:121], v[120:121], v[192:193], v[80:81] op_sel_hi:[1,0,1]
	v_pk_fma_f32 v[122:123], v[122:123], v[192:193], v[82:83] op_sel_hi:[1,0,1]
	v_pk_fma_f32 v[116:117], v[116:117], v[192:193], v[76:77] op_sel_hi:[1,0,1]
	v_pk_fma_f32 v[118:119], v[118:119], v[192:193], v[78:79] op_sel_hi:[1,0,1]
	v_pk_fma_f32 v[112:113], v[112:113], v[192:193], v[72:73] op_sel_hi:[1,0,1]
	v_pk_fma_f32 v[114:115], v[114:115], v[192:193], v[74:75] op_sel_hi:[1,0,1]
	v_max_f32_e32 v124, 0, v124
	v_max_f32_e32 v125, 0, v125
	v_max_f32_e32 v126, 0, v126
	v_max_f32_e32 v127, 0, v127
	v_max_f32_e32 v120, 0, v120
	v_max_f32_e32 v121, 0, v121
	v_max_f32_e32 v122, 0, v122
	v_max_f32_e32 v123, 0, v123
	v_max_f32_e32 v116, 0, v116
	v_max_f32_e32 v117, 0, v117
	v_max_f32_e32 v118, 0, v118
	v_max_f32_e32 v119, 0, v119
	v_max_f32_e32 v112, 0, v112
	v_max_f32_e32 v113, 0, v113
	v_max_f32_e32 v114, 0, v114
	v_max_f32_e32 v115, 0, v115
	v_pk_mul_f32 v[124:125], v[124:125], v[124:125]
	v_pk_mul_f32 v[126:127], v[126:127], v[126:127]
	v_pk_mul_f32 v[120:121], v[120:121], v[120:121]
	v_pk_mul_f32 v[122:123], v[122:123], v[122:123]
	v_pk_mul_f32 v[116:117], v[116:117], v[116:117]
	v_pk_mul_f32 v[118:119], v[118:119], v[118:119]
	v_pk_mul_f32 v[112:113], v[112:113], v[112:113]
	v_pk_mul_f32 v[114:115], v[114:115], v[114:115]
	v_cvt_pk_bf16_f32 v124, v124, v125
	v_cvt_pk_bf16_f32 v125, v126, v127
	v_cvt_pk_bf16_f32 v126, v120, v121
	v_cvt_pk_bf16_f32 v127, v122, v123
	v_cvt_pk_bf16_f32 v116, v116, v117
	v_cvt_pk_bf16_f32 v117, v118, v119
	v_cvt_pk_bf16_f32 v118, v112, v113
	v_cvt_pk_bf16_f32 v119, v114, v115
	ds_bpermute_b32 v208, v198, v124
	ds_bpermute_b32 v209, v198, v125
	ds_bpermute_b32 v210, v198, v126
	ds_bpermute_b32 v211, v198, v127
	s_waitcnt lgkmcnt(4)
	global_store_dwordx4 v191, v[216:219], s[18:19]
	global_store_dwordx4 v191, v[220:223], s[18:19] offset:256
	s_add_u32 s18, s18, 0x20000
	s_addc_u32 s19, s19, 0
	ds_bpermute_b32 v212, v198, v116
	ds_bpermute_b32 v213, v198, v117
	ds_bpermute_b32 v214, v198, v118
	ds_bpermute_b32 v215, v198, v119
	v_mov_b32_e32 v192, v185
	v_pk_fma_f32 v[108:109], v[108:109], v[192:193], v[84:85] op_sel_hi:[1,0,1]
	v_pk_fma_f32 v[110:111], v[110:111], v[192:193], v[86:87] op_sel_hi:[1,0,1]
	v_pk_fma_f32 v[104:105], v[104:105], v[192:193], v[80:81] op_sel_hi:[1,0,1]
	v_pk_fma_f32 v[106:107], v[106:107], v[192:193], v[82:83] op_sel_hi:[1,0,1]
	v_pk_fma_f32 v[100:101], v[100:101], v[192:193], v[76:77] op_sel_hi:[1,0,1]
	v_pk_fma_f32 v[102:103], v[102:103], v[192:193], v[78:79] op_sel_hi:[1,0,1]
	v_pk_fma_f32 v[96:97], v[96:97], v[192:193], v[72:73] op_sel_hi:[1,0,1]
	v_pk_fma_f32 v[98:99], v[98:99], v[192:193], v[74:75] op_sel_hi:[1,0,1]
	v_max_f32_e32 v108, 0, v108
	v_max_f32_e32 v109, 0, v109
	v_max_f32_e32 v110, 0, v110
	v_max_f32_e32 v111, 0, v111
	v_max_f32_e32 v104, 0, v104
	v_max_f32_e32 v105, 0, v105
	v_max_f32_e32 v106, 0, v106
	v_max_f32_e32 v107, 0, v107
	v_max_f32_e32 v100, 0, v100
	v_max_f32_e32 v101, 0, v101
	v_max_f32_e32 v102, 0, v102
	v_max_f32_e32 v103, 0, v103
	v_max_f32_e32 v96, 0, v96
	v_max_f32_e32 v97, 0, v97
	v_max_f32_e32 v98, 0, v98
	v_max_f32_e32 v99, 0, v99
	v_pk_mul_f32 v[108:109], v[108:109], v[108:109]
	v_pk_mul_f32 v[110:111], v[110:111], v[110:111]
	v_pk_mul_f32 v[104:105], v[104:105], v[104:105]
	v_pk_mul_f32 v[106:107], v[106:107], v[106:107]
	v_pk_mul_f32 v[100:101], v[100:101], v[100:101]
	v_pk_mul_f32 v[102:103], v[102:103], v[102:103]
	v_pk_mul_f32 v[96:97], v[96:97], v[96:97]
	v_pk_mul_f32 v[98:99], v[98:99], v[98:99]
	v_cvt_pk_bf16_f32 v108, v108, v109
	v_cvt_pk_bf16_f32 v109, v110, v111
	v_cvt_pk_bf16_f32 v110, v104, v105
	v_cvt_pk_bf16_f32 v111, v106, v107
	v_cvt_pk_bf16_f32 v100, v100, v101
	v_cvt_pk_bf16_f32 v101, v102, v103
	v_cvt_pk_bf16_f32 v102, v96, v97
	v_cvt_pk_bf16_f32 v103, v98, v99
	ds_bpermute_b32 v216, v198, v108
	ds_bpermute_b32 v217, v198, v109
	ds_bpermute_b32 v218, v198, v110
	ds_bpermute_b32 v219, v198, v111
	s_waitcnt lgkmcnt(4)
	global_store_dwordx4 v191, v[208:211], s[18:19]
	global_store_dwordx4 v191, v[212:215], s[18:19] offset:256
	s_add_u32 s18, s18, 0x20000
	s_addc_u32 s19, s19, 0
	ds_bpermute_b32 v220, v198, v100
	ds_bpermute_b32 v221, v198, v101
	ds_bpermute_b32 v222, v198, v102
	ds_bpermute_b32 v223, v198, v103
	v_mov_b32_e32 v192, v186
	v_pk_fma_f32 v[92:93], v[92:93], v[192:193], v[84:85] op_sel_hi:[1,0,1]
	v_pk_fma_f32 v[94:95], v[94:95], v[192:193], v[86:87] op_sel_hi:[1,0,1]
	v_pk_fma_f32 v[88:89], v[88:89], v[192:193], v[80:81] op_sel_hi:[1,0,1]
	v_pk_fma_f32 v[90:91], v[90:91], v[192:193], v[82:83] op_sel_hi:[1,0,1]
	v_pk_fma_f32 v[68:69], v[68:69], v[192:193], v[76:77] op_sel_hi:[1,0,1]
	v_pk_fma_f32 v[70:71], v[70:71], v[192:193], v[78:79] op_sel_hi:[1,0,1]
	v_pk_fma_f32 v[64:65], v[64:65], v[192:193], v[72:73] op_sel_hi:[1,0,1]
	v_pk_fma_f32 v[66:67], v[66:67], v[192:193], v[74:75] op_sel_hi:[1,0,1]
	v_max_f32_e32 v92, 0, v92
	v_max_f32_e32 v93, 0, v93
	v_max_f32_e32 v94, 0, v94
	v_max_f32_e32 v95, 0, v95
	v_max_f32_e32 v88, 0, v88
	v_max_f32_e32 v89, 0, v89
	v_max_f32_e32 v90, 0, v90
	v_max_f32_e32 v91, 0, v91
	v_max_f32_e32 v68, 0, v68
	v_max_f32_e32 v69, 0, v69
	v_max_f32_e32 v70, 0, v70
	v_max_f32_e32 v71, 0, v71
	v_max_f32_e32 v64, 0, v64
	v_max_f32_e32 v65, 0, v65
	v_max_f32_e32 v66, 0, v66
	v_max_f32_e32 v67, 0, v67
	v_pk_mul_f32 v[92:93], v[92:93], v[92:93]
	v_pk_mul_f32 v[94:95], v[94:95], v[94:95]
	v_pk_mul_f32 v[88:89], v[88:89], v[88:89]
	v_pk_mul_f32 v[90:91], v[90:91], v[90:91]
	v_pk_mul_f32 v[68:69], v[68:69], v[68:69]
	v_pk_mul_f32 v[70:71], v[70:71], v[70:71]
	v_pk_mul_f32 v[64:65], v[64:65], v[64:65]
	v_pk_mul_f32 v[66:67], v[66:67], v[66:67]
	v_cvt_pk_bf16_f32 v92, v92, v93
	v_cvt_pk_bf16_f32 v93, v94, v95
	v_cvt_pk_bf16_f32 v94, v88, v89
	v_cvt_pk_bf16_f32 v95, v90, v91
	v_cvt_pk_bf16_f32 v68, v68, v69
	v_cvt_pk_bf16_f32 v69, v70, v71
	v_cvt_pk_bf16_f32 v70, v64, v65
	v_cvt_pk_bf16_f32 v71, v66, v67
	ds_bpermute_b32 v208, v198, v92
	ds_bpermute_b32 v209, v198, v93
	ds_bpermute_b32 v210, v198, v94
	ds_bpermute_b32 v211, v198, v95
	s_waitcnt lgkmcnt(4)
	global_store_dwordx4 v191, v[216:219], s[18:19]
	global_store_dwordx4 v191, v[220:223], s[18:19] offset:256
	s_add_u32 s18, s18, 0x20000
	s_addc_u32 s19, s19, 0
	ds_bpermute_b32 v212, v198, v68
	ds_bpermute_b32 v213, v198, v69
	ds_bpermute_b32 v214, v198, v70
	ds_bpermute_b32 v215, v198, v71
	v_mov_b32_e32 v192, v187
	v_pk_fma_f32 v[60:61], v[60:61], v[192:193], v[84:85] op_sel_hi:[1,0,1]
	v_pk_fma_f32 v[62:63], v[62:63], v[192:193], v[86:87] op_sel_hi:[1,0,1]
	v_pk_fma_f32 v[56:57], v[56:57], v[192:193], v[80:81] op_sel_hi:[1,0,1]
	v_pk_fma_f32 v[58:59], v[58:59], v[192:193], v[82:83] op_sel_hi:[1,0,1]
	v_pk_fma_f32 v[52:53], v[52:53], v[192:193], v[76:77] op_sel_hi:[1,0,1]
	v_pk_fma_f32 v[54:55], v[54:55], v[192:193], v[78:79] op_sel_hi:[1,0,1]
	v_pk_fma_f32 v[48:49], v[48:49], v[192:193], v[72:73] op_sel_hi:[1,0,1]
	v_pk_fma_f32 v[50:51], v[50:51], v[192:193], v[74:75] op_sel_hi:[1,0,1]
	v_max_f32_e32 v60, 0, v60
	v_max_f32_e32 v61, 0, v61
	v_max_f32_e32 v62, 0, v62
	v_max_f32_e32 v63, 0, v63
	v_max_f32_e32 v56, 0, v56
	v_max_f32_e32 v57, 0, v57
	v_max_f32_e32 v58, 0, v58
	v_max_f32_e32 v59, 0, v59
	v_max_f32_e32 v52, 0, v52
	v_max_f32_e32 v53, 0, v53
	v_max_f32_e32 v54, 0, v54
	v_max_f32_e32 v55, 0, v55
	v_max_f32_e32 v48, 0, v48
	v_max_f32_e32 v49, 0, v49
	v_max_f32_e32 v50, 0, v50
	v_max_f32_e32 v51, 0, v51
	v_pk_mul_f32 v[60:61], v[60:61], v[60:61]
	v_pk_mul_f32 v[62:63], v[62:63], v[62:63]
	v_pk_mul_f32 v[56:57], v[56:57], v[56:57]
	v_pk_mul_f32 v[58:59], v[58:59], v[58:59]
	v_pk_mul_f32 v[52:53], v[52:53], v[52:53]
	v_pk_mul_f32 v[54:55], v[54:55], v[54:55]
	v_pk_mul_f32 v[48:49], v[48:49], v[48:49]
	v_pk_mul_f32 v[50:51], v[50:51], v[50:51]
	v_cvt_pk_bf16_f32 v60, v60, v61
	v_cvt_pk_bf16_f32 v61, v62, v63
	v_cvt_pk_bf16_f32 v62, v56, v57
	v_cvt_pk_bf16_f32 v63, v58, v59
	v_cvt_pk_bf16_f32 v52, v52, v53
	v_cvt_pk_bf16_f32 v53, v54, v55
	v_cvt_pk_bf16_f32 v54, v48, v49
	v_cvt_pk_bf16_f32 v55, v50, v51
	ds_bpermute_b32 v216, v198, v60
	ds_bpermute_b32 v217, v198, v61
	ds_bpermute_b32 v218, v198, v62
	ds_bpermute_b32 v219, v198, v63
	s_waitcnt lgkmcnt(4)
	global_store_dwordx4 v191, v[208:211], s[18:19]
	global_store_dwordx4 v191, v[212:215], s[18:19] offset:256
	s_add_u32 s18, s18, 0xa0000
	s_addc_u32 s19, s19, 0
	ds_bpermute_b32 v220, v198, v52
	ds_bpermute_b32 v221, v198, v53
	ds_bpermute_b32 v222, v198, v54
	ds_bpermute_b32 v223, v198, v55
	v_mov_b32_e32 v192, v188
	v_pk_fma_f32 v[44:45], v[44:45], v[192:193], v[84:85] op_sel_hi:[1,0,1]
	v_pk_fma_f32 v[46:47], v[46:47], v[192:193], v[86:87] op_sel_hi:[1,0,1]
	v_pk_fma_f32 v[40:41], v[40:41], v[192:193], v[80:81] op_sel_hi:[1,0,1]
	v_pk_fma_f32 v[42:43], v[42:43], v[192:193], v[82:83] op_sel_hi:[1,0,1]
	v_pk_fma_f32 v[36:37], v[36:37], v[192:193], v[76:77] op_sel_hi:[1,0,1]
	v_pk_fma_f32 v[38:39], v[38:39], v[192:193], v[78:79] op_sel_hi:[1,0,1]
	v_pk_fma_f32 v[32:33], v[32:33], v[192:193], v[72:73] op_sel_hi:[1,0,1]
	v_pk_fma_f32 v[34:35], v[34:35], v[192:193], v[74:75] op_sel_hi:[1,0,1]
	v_max_f32_e32 v44, 0, v44
	v_max_f32_e32 v45, 0, v45
	v_max_f32_e32 v46, 0, v46
	v_max_f32_e32 v47, 0, v47
	v_max_f32_e32 v40, 0, v40
	v_max_f32_e32 v41, 0, v41
	v_max_f32_e32 v42, 0, v42
	v_max_f32_e32 v43, 0, v43
	v_max_f32_e32 v36, 0, v36
	v_max_f32_e32 v37, 0, v37
	v_max_f32_e32 v38, 0, v38
	v_max_f32_e32 v39, 0, v39
	v_max_f32_e32 v32, 0, v32
	v_max_f32_e32 v33, 0, v33
	v_max_f32_e32 v34, 0, v34
	v_max_f32_e32 v35, 0, v35
	v_pk_mul_f32 v[44:45], v[44:45], v[44:45]
	v_pk_mul_f32 v[46:47], v[46:47], v[46:47]
	v_pk_mul_f32 v[40:41], v[40:41], v[40:41]
	v_pk_mul_f32 v[42:43], v[42:43], v[42:43]
	v_pk_mul_f32 v[36:37], v[36:37], v[36:37]
	v_pk_mul_f32 v[38:39], v[38:39], v[38:39]
	v_pk_mul_f32 v[32:33], v[32:33], v[32:33]
	v_pk_mul_f32 v[34:35], v[34:35], v[34:35]
	v_cvt_pk_bf16_f32 v44, v44, v45
	v_cvt_pk_bf16_f32 v45, v46, v47
	v_cvt_pk_bf16_f32 v46, v40, v41
	v_cvt_pk_bf16_f32 v47, v42, v43
	v_cvt_pk_bf16_f32 v36, v36, v37
	v_cvt_pk_bf16_f32 v37, v38, v39
	v_cvt_pk_bf16_f32 v38, v32, v33
	v_cvt_pk_bf16_f32 v39, v34, v35
	ds_bpermute_b32 v208, v198, v44
	ds_bpermute_b32 v209, v198, v45
	ds_bpermute_b32 v210, v198, v46
	ds_bpermute_b32 v211, v198, v47
	s_waitcnt lgkmcnt(4)
	global_store_dwordx4 v191, v[216:219], s[18:19]
	global_store_dwordx4 v191, v[220:223], s[18:19] offset:256
	s_add_u32 s18, s18, 0x20000
	s_addc_u32 s19, s19, 0
	ds_bpermute_b32 v212, v198, v36
	ds_bpermute_b32 v213, v198, v37
	ds_bpermute_b32 v214, v198, v38
	ds_bpermute_b32 v215, v198, v39
	v_mov_b32_e32 v192, v189
	v_pk_fma_f32 v[28:29], v[28:29], v[192:193], v[84:85] op_sel_hi:[1,0,1]
	v_pk_fma_f32 v[30:31], v[30:31], v[192:193], v[86:87] op_sel_hi:[1,0,1]
	v_pk_fma_f32 v[24:25], v[24:25], v[192:193], v[80:81] op_sel_hi:[1,0,1]
	v_pk_fma_f32 v[26:27], v[26:27], v[192:193], v[82:83] op_sel_hi:[1,0,1]
	v_pk_fma_f32 v[20:21], v[20:21], v[192:193], v[76:77] op_sel_hi:[1,0,1]
	v_pk_fma_f32 v[22:23], v[22:23], v[192:193], v[78:79] op_sel_hi:[1,0,1]
	v_pk_fma_f32 v[16:17], v[16:17], v[192:193], v[72:73] op_sel_hi:[1,0,1]
	v_pk_fma_f32 v[18:19], v[18:19], v[192:193], v[74:75] op_sel_hi:[1,0,1]
	v_max_f32_e32 v28, 0, v28
	v_max_f32_e32 v29, 0, v29
	v_max_f32_e32 v30, 0, v30
	v_max_f32_e32 v31, 0, v31
	v_max_f32_e32 v24, 0, v24
	v_max_f32_e32 v25, 0, v25
	v_max_f32_e32 v26, 0, v26
	v_max_f32_e32 v27, 0, v27
	v_max_f32_e32 v20, 0, v20
	v_max_f32_e32 v21, 0, v21
	v_max_f32_e32 v22, 0, v22
	v_max_f32_e32 v23, 0, v23
	v_max_f32_e32 v16, 0, v16
	v_max_f32_e32 v17, 0, v17
	v_max_f32_e32 v18, 0, v18
	v_max_f32_e32 v19, 0, v19
	v_pk_mul_f32 v[28:29], v[28:29], v[28:29]
	v_pk_mul_f32 v[30:31], v[30:31], v[30:31]
	v_pk_mul_f32 v[24:25], v[24:25], v[24:25]
	v_pk_mul_f32 v[26:27], v[26:27], v[26:27]
	v_pk_mul_f32 v[20:21], v[20:21], v[20:21]
	v_pk_mul_f32 v[22:23], v[22:23], v[22:23]
	v_pk_mul_f32 v[16:17], v[16:17], v[16:17]
	v_pk_mul_f32 v[18:19], v[18:19], v[18:19]
	v_cvt_pk_bf16_f32 v28, v28, v29
	v_cvt_pk_bf16_f32 v29, v30, v31
	v_cvt_pk_bf16_f32 v30, v24, v25
	v_cvt_pk_bf16_f32 v31, v26, v27
	v_cvt_pk_bf16_f32 v20, v20, v21
	v_cvt_pk_bf16_f32 v21, v22, v23
	v_cvt_pk_bf16_f32 v22, v16, v17
	v_cvt_pk_bf16_f32 v23, v18, v19
	ds_bpermute_b32 v216, v198, v28
	ds_bpermute_b32 v217, v198, v29
	ds_bpermute_b32 v218, v198, v30
	ds_bpermute_b32 v219, v198, v31
	s_waitcnt lgkmcnt(4)
	global_store_dwordx4 v191, v[208:211], s[18:19]
	global_store_dwordx4 v191, v[212:215], s[18:19] offset:256
	s_add_u32 s18, s18, 0x20000
	s_addc_u32 s19, s19, 0
	ds_bpermute_b32 v220, v198, v20
	ds_bpermute_b32 v221, v198, v21
	ds_bpermute_b32 v222, v198, v22
	ds_bpermute_b32 v223, v198, v23
	v_mov_b32_e32 v192, v190
	v_pk_fma_f32 v[12:13], v[12:13], v[192:193], v[84:85] op_sel_hi:[1,0,1]
	v_pk_fma_f32 v[14:15], v[14:15], v[192:193], v[86:87] op_sel_hi:[1,0,1]
	v_pk_fma_f32 v[8:9], v[8:9], v[192:193], v[80:81] op_sel_hi:[1,0,1]
	v_pk_fma_f32 v[10:11], v[10:11], v[192:193], v[82:83] op_sel_hi:[1,0,1]
	v_pk_fma_f32 v[4:5], v[4:5], v[192:193], v[76:77] op_sel_hi:[1,0,1]
	v_pk_fma_f32 v[6:7], v[6:7], v[192:193], v[78:79] op_sel_hi:[1,0,1]
	v_pk_fma_f32 v[0:1], v[0:1], v[192:193], v[72:73] op_sel_hi:[1,0,1]
	v_pk_fma_f32 v[2:3], v[2:3], v[192:193], v[74:75] op_sel_hi:[1,0,1]
	v_max_f32_e32 v12, 0, v12
	v_max_f32_e32 v13, 0, v13
	v_max_f32_e32 v14, 0, v14
	v_max_f32_e32 v15, 0, v15
	v_max_f32_e32 v8, 0, v8
	v_max_f32_e32 v9, 0, v9
	v_max_f32_e32 v10, 0, v10
	v_max_f32_e32 v11, 0, v11
	v_max_f32_e32 v4, 0, v4
	v_max_f32_e32 v5, 0, v5
	v_max_f32_e32 v6, 0, v6
	v_max_f32_e32 v7, 0, v7
	v_max_f32_e32 v0, 0, v0
	v_max_f32_e32 v1, 0, v1
	v_max_f32_e32 v2, 0, v2
	v_max_f32_e32 v3, 0, v3
	v_pk_mul_f32 v[12:13], v[12:13], v[12:13]
	v_pk_mul_f32 v[14:15], v[14:15], v[14:15]
	v_pk_mul_f32 v[8:9], v[8:9], v[8:9]
	v_pk_mul_f32 v[10:11], v[10:11], v[10:11]
	v_pk_mul_f32 v[4:5], v[4:5], v[4:5]
	v_pk_mul_f32 v[6:7], v[6:7], v[6:7]
	v_pk_mul_f32 v[0:1], v[0:1], v[0:1]
	v_pk_mul_f32 v[2:3], v[2:3], v[2:3]
	v_cvt_pk_bf16_f32 v12, v12, v13
	v_cvt_pk_bf16_f32 v13, v14, v15
	v_cvt_pk_bf16_f32 v14, v8, v9
	v_cvt_pk_bf16_f32 v15, v10, v11
	v_cvt_pk_bf16_f32 v4, v4, v5
	v_cvt_pk_bf16_f32 v5, v6, v7
	v_cvt_pk_bf16_f32 v6, v0, v1
	v_cvt_pk_bf16_f32 v7, v2, v3
	ds_bpermute_b32 v208, v198, v12
	ds_bpermute_b32 v209, v198, v13
	ds_bpermute_b32 v210, v198, v14
	ds_bpermute_b32 v211, v198, v15
	s_waitcnt lgkmcnt(4)
	global_store_dwordx4 v191, v[216:219], s[18:19]
	global_store_dwordx4 v191, v[220:223], s[18:19] offset:256
	s_add_u32 s18, s18, 0x20000
	s_addc_u32 s19, s19, 0
	ds_bpermute_b32 v212, v198, v4
	ds_bpermute_b32 v213, v198, v5
	ds_bpermute_b32 v214, v198, v6
	ds_bpermute_b32 v215, v198, v7
	s_waitcnt lgkmcnt(0)
	global_store_dwordx4 v191, v[208:211], s[18:19]
	global_store_dwordx4 v191, v[212:215], s[18:19] offset:256
	s_andn2_b64 vcc, exec, s[2:3]
	s_mov_b64 s[2:3], -1
	s_cbranch_vccnz .LBB0_1172
	s_andn2_b64 vcc, exec, s[4:5]
	s_cbranch_vccnz .LBB0_1171
	s_barrier
	s_branch .LBB0_1171
